# speedup vs baseline: 1.0069x; 1.0069x over previous
.LBB0_331:
	s_cbranch_execz .LBB0_249
	v_readlane_b32 s34, v252, 16
	v_readlane_b32 s35, v252, 17
	s_cmp_lt_i32 s35, 2
	s_cbranch_scc1 .LBB0_371
	s_waitcnt vmcnt(0)
	v_cmp_eq_u32_e32 vcc, 0, v1
	s_waitcnt vmcnt(0)
	s_barrier
	s_and_saveexec_b64 s[0:1], vcc
	s_cbranch_execz .LBB0_370
	s_cmp_lg_u32 s101, 0
	s_cbranch_scc1 .Lxl_glob_1
	s_and_b32 s6, s2, 7
	v_mov_b32_e32 v2, 0
	v_mov_b32_e32 v3, 1
	s_nop 3
	s_lshl_b32 s3, s6, 8
	s_add_u32 s4, s86, s3
	s_addc_u32 s5, s87, 0
	s_add_u32 s4, s4, 0x2b00480
	s_addc_u32 s5, s5, 0
	s_mov_b32 s98, 0
	global_atomic_add v3, v2, v3, s[4:5] sc0
	buffer_inv sc1
	s_waitcnt vmcnt(0)
	v_add_u32_e32 v3, 1, v3
	v_cmp_gt_u32_e32 vcc, s100, v3
	s_cbranch_vccz .Lxl_exit_1

.Lxl_exit_1:
	s_nop 0
	s_branch .LBB0_370

.LBB0_496:
	s_cbranch_execz .LBB0_484
	v_readlane_b32 s34, v252, 16
	v_readlane_b32 s35, v252, 17
	s_cmp_lt_i32 s35, 4
	s_cbranch_scc1 .LBB0_536
	s_waitcnt vmcnt(0)
	v_cmp_eq_u32_e32 vcc, 0, v1
	s_waitcnt vmcnt(0)
	s_barrier
	s_and_saveexec_b64 s[0:1], vcc
	s_cbranch_execz .LBB0_535
	s_cmp_lg_u32 s101, 0
	s_cbranch_scc1 .Lxl_glob_3
	s_and_b32 s6, s2, 7
	v_mov_b32_e32 v2, 0
	v_mov_b32_e32 v3, 1
	s_nop 3
	s_lshl_b32 s3, s6, 8
	s_add_u32 s4, s86, s3
	s_addc_u32 s5, s87, 0
	s_add_u32 s4, s4, 0x2b00498
	s_addc_u32 s5, s5, 0
	s_mov_b32 s98, 0
	global_atomic_add v3, v2, v3, s[4:5] sc0
	buffer_inv sc1
	s_waitcnt vmcnt(0)
	v_add_u32_e32 v3, 1, v3
	v_cmp_gt_u32_e32 vcc, s100, v3
	s_cbranch_vccz .Lxl_exit_3

.LBB0_550:
	s_cbranch_execz .LBB0_539
	v_readlane_b32 s34, v252, 16
	v_readlane_b32 s35, v252, 17
	s_cmp_lt_i32 s35, 5
	s_cbranch_scc1 .LBB0_590
	s_waitcnt vmcnt(0)
	v_cmp_eq_u32_e32 vcc, 0, v1
	s_waitcnt vmcnt(0)
	s_barrier
	s_and_saveexec_b64 s[0:1], vcc
	s_cbranch_execz .LBB0_589
	s_cmp_lg_u32 s101, 0
	s_cbranch_scc1 .Lxl_glob_4
	s_and_b32 s6, s2, 7
	v_mov_b32_e32 v2, 0
	v_mov_b32_e32 v3, 1
	s_nop 3
	s_lshl_b32 s3, s6, 8
	s_add_u32 s4, s86, s3
	s_addc_u32 s5, s87, 0
	s_add_u32 s4, s4, 0x2b00484
	s_addc_u32 s5, s5, 0
	s_mov_b32 s98, 0
	global_atomic_add v3, v2, v3, s[4:5] sc0
	buffer_inv sc1
	s_waitcnt vmcnt(0)
	v_add_u32_e32 v3, 1, v3
	v_cmp_gt_u32_e32 vcc, s100, v3
	s_cbranch_vccz .Lxl_exit_4

.LBB0_620:
	s_cbranch_execz .LBB0_593
	v_readlane_b32 s34, v252, 16
	v_readlane_b32 s35, v252, 17
	s_cmp_lt_i32 s35, 6
	s_cbranch_scc1 .LBB0_660
	s_waitcnt vmcnt(0)
	v_cmp_eq_u32_e32 vcc, 0, v1
	s_waitcnt vmcnt(0) lgkmcnt(0)
	s_barrier
	s_and_saveexec_b64 s[0:1], vcc
	s_cbranch_execz .LBB0_659
	s_cmp_lg_u32 s101, 0
	s_cbranch_scc1 .Lxl_glob_5
	s_and_b32 s6, s2, 7
	v_mov_b32_e32 v2, 0
	v_mov_b32_e32 v3, 1
	s_nop 3
	s_lshl_b32 s3, s6, 8
	s_add_u32 s4, s86, s3
	s_addc_u32 s5, s87, 0
	s_add_u32 s4, s4, 0x2b00488
	s_addc_u32 s5, s5, 0
	s_mov_b32 s98, 0
	global_atomic_add v3, v2, v3, s[4:5] sc0
	buffer_inv sc1
	s_waitcnt vmcnt(0)
	v_add_u32_e32 v3, 1, v3
	v_cmp_gt_u32_e32 vcc, s100, v3
	s_cbranch_vccz .Lxl_exit_5

.LBB0_669:
	v_readlane_b32 s34, v252, 16
	v_readlane_b32 s35, v252, 17
	s_cmp_lt_i32 s35, 7
	s_cbranch_scc1 .LBB0_708
	s_waitcnt vmcnt(0)
	v_cmp_eq_u32_e32 vcc, 0, v1
	s_waitcnt vmcnt(0)
	s_barrier
	s_and_saveexec_b64 s[0:1], vcc
	s_cbranch_execz .LBB0_707
	s_cmp_lg_u32 s101, 0
	s_cbranch_scc1 .Lxl_glob_6
	s_and_b32 s6, s2, 7
	v_mov_b32_e32 v2, 0
	v_mov_b32_e32 v3, 1
	s_nop 3
	s_lshl_b32 s3, s6, 8
	s_add_u32 s4, s86, s3
	s_addc_u32 s5, s87, 0
	s_add_u32 s4, s4, 0x2b0048c
	s_addc_u32 s5, s5, 0
	s_mov_b32 s98, 0
	global_atomic_add v3, v2, v3, s[4:5] sc0
	buffer_inv sc1
	s_waitcnt vmcnt(0)
	v_add_u32_e32 v3, 1, v3
	v_cmp_gt_u32_e32 vcc, s100, v3
	s_cbranch_vccz .Lxl_exit_6

.LBB0_1027:
	v_readlane_b32 s34, v252, 16
	v_readlane_b32 s35, v252, 17
	s_cmp_lt_i32 s35, 10
	s_cbranch_scc1 .LBB0_1066
	s_waitcnt vmcnt(0)
	v_cmp_eq_u32_e32 vcc, 0, v1
	s_waitcnt vmcnt(0)
	s_barrier
	s_and_saveexec_b64 s[0:1], vcc
	s_cbranch_execz .LBB0_1065
	s_cmp_lg_u32 s101, 0
	s_cbranch_scc1 .Lxl_glob_9
	s_and_b32 s6, s2, 7
	v_mov_b32_e32 v2, 0
	v_mov_b32_e32 v3, 1
	s_nop 3
	s_lshl_b32 s3, s6, 8
	s_add_u32 s4, s86, s3
	s_addc_u32 s5, s87, 0
	s_add_u32 s4, s4, 0x2b0049c
	s_addc_u32 s5, s5, 0
	s_mov_b32 s98, 0
	global_atomic_add v3, v2, v3, s[4:5] sc0
	buffer_inv sc1
	s_waitcnt vmcnt(0)
	v_add_u32_e32 v3, 1, v3
	v_cmp_gt_u32_e32 vcc, s100, v3
	s_cbranch_vccz .Lxl_exit_9

.LBB0_1104:
	s_cbranch_execz .LBB0_1070
	v_readlane_b32 s34, v252, 16
	v_readlane_b32 s35, v252, 17
	s_cmp_lt_i32 s35, 11
	s_cbranch_scc1 .LBB0_1144
	s_waitcnt vmcnt(0)
	v_cmp_eq_u32_e32 vcc, 0, v1
	s_waitcnt vmcnt(0) lgkmcnt(0)
	s_barrier
	s_and_saveexec_b64 s[0:1], vcc
	s_cbranch_execz .LBB0_1143
	s_cmp_lg_u32 s101, 0
	s_cbranch_scc1 .Lxl_glob_10
	s_and_b32 s6, s2, 7
	v_mov_b32_e32 v2, 0
	v_mov_b32_e32 v3, 1
	s_nop 3
	s_lshl_b32 s3, s6, 8
	s_add_u32 s4, s86, s3
	s_addc_u32 s5, s87, 0
	s_add_u32 s4, s4, 0x2b00490
	s_addc_u32 s5, s5, 0
	s_mov_b32 s98, 0
	global_atomic_add v3, v2, v3, s[4:5] sc0
	buffer_inv sc1
	s_waitcnt vmcnt(0)
	v_add_u32_e32 v3, 1, v3
	v_cmp_gt_u32_e32 vcc, s100, v3
	s_cbranch_vccz .Lxl_exit_10

.LBB0_1153:
	v_readlane_b32 s34, v252, 16
	v_readlane_b32 s35, v252, 17
	s_cmp_lt_i32 s35, 12
	s_cbranch_scc1 .LBB0_1192
	s_waitcnt vmcnt(0)
	v_cmp_eq_u32_e32 vcc, 0, v1
	s_waitcnt vmcnt(0)
	s_barrier
	s_and_saveexec_b64 s[0:1], vcc
	s_cbranch_execz .LBB0_1191
	s_cmp_lg_u32 s101, 0
	s_cbranch_scc1 .Lxl_glob_11
	s_and_b32 s6, s2, 7
	v_mov_b32_e32 v2, 0
	v_mov_b32_e32 v3, 1
	s_nop 3
	s_lshl_b32 s3, s6, 8
	s_add_u32 s4, s86, s3
	s_addc_u32 s5, s87, 0
	s_add_u32 s4, s4, 0x2b00494
	s_addc_u32 s5, s5, 0
	s_mov_b32 s98, 0
	global_atomic_add v3, v2, v3, s[4:5] sc0
	buffer_inv sc1
	s_waitcnt vmcnt(0)
	v_add_u32_e32 v3, 1, v3
	v_cmp_gt_u32_e32 vcc, s100, v3
	s_cbranch_vccz .Lxl_exit_11
